# merge-phase K-loop: remaining LDS-DMA address VALU removed as well (scalar T pairs)
# speedup vs baseline: 1.0128x; 1.0029x over previous
; #define PG8_STAGE(bufoff, gbase, voff) do { _Pragma("unroll") for (int _i = 0; _i < 2; ++_i) \
;         __builtin_amdgcn_global_load_lds((const unsigned*)((const char*)(gbase) + (voff)[_i]), (LAS unsigned*)(lds + (bufoff) + ldsw + _i * 8192), 16, 0, 0); } while (0)
; #define PG8_LDA(dst, b, h) do { _Pragma("unroll") for (int m = 0; m < 4; ++m) _Pragma("unroll") for (int k = 0; k < 2; ++k) dst[m][k] = *(const LAS bf16x8*)(lds + PG8_SA(b, h) + aoff + m * 2048 + k * 1024); } while (0)
; #define PG8_MMA(ai, bj, At, Bt) do { __builtin_amdgcn_s_setprio(1); _Pragma("unroll") for (int m = 0; m < 4; ++m) _Pragma("unroll") for (int n = 0; n < 2; ++n) _Pragma("unroll") for (int k = 0; k < 2; ++k) \
;         acc[ai][bj][m][n] = __builtin_amdgcn_mfma_f32_16x16x32_bf16(Bt[n][k], At[m][k], acc[ai][bj][m][n], 0, 0, 0); __builtin_amdgcn_s_setprio(0); } while (0)
; #define PG8_WAIT_V(n) asm volatile("s_waitcnt vmcnt(" #n ")" ::: "memory")
; #define PG8_WAIT_L(n) asm volatile("s_waitcnt lgkmcnt(" #n ")" ::: "memory")
; #define PG8_BAR __builtin_amdgcn_s_barrier()
; #define PG8_SCHED __builtin_amdgcn_sched_barrier(0)
; template <class Epi, class Sched>
; DI void gemm_phase(LAS unsigned char* lds, const Gemm g, const Sched& S, const Epi& E) {
;     ...
;             PG8_WAIT_V(8); PG8_WAIT_L(0); PG8_BAR; PG8_MMA(0, 0, At, B0); PG8_MMA(0, 1, At, B1); PG8_BAR; PG8_SCHED;
;             PG8_LDA(At, 0, 1); PG8_STAGE(PG8_SB(0, 0), b2, voffB); PG8_STAGE(PG8_SB(0, 1), b2 + hstepB, voffB); PG8_STAGE(PG8_SA(0, 0), a2, voffA);
;             PG8_WAIT_V(8); PG8_WAIT_L(0); PG8_BAR; PG8_MMA(1, 0, At, B0); PG8_MMA(1, 1, At, B1); PG8_BAR; PG8_SCHED;
.Lpk3_w1:
	s_waitcnt lgkmcnt(0)
	s_barrier
	s_setprio 1
	v_mfma_f32_16x16x32_bf16 v[126:129], v[146:149], v[186:189], v[126:129]
	v_mfma_f32_16x16x32_bf16 v[122:125], v[154:157], v[186:189], v[122:125]
	v_mfma_f32_16x16x32_bf16 v[118:121], v[146:149], v[194:197], v[118:121]
	v_mfma_f32_16x16x32_bf16 v[114:117], v[154:157], v[194:197], v[114:117]
	v_mfma_f32_16x16x32_bf16 v[110:113], v[146:149], v[202:205], v[110:113]
	v_mfma_f32_16x16x32_bf16 v[106:109], v[154:157], v[202:205], v[106:109]
	v_mfma_f32_16x16x32_bf16 v[102:105], v[146:149], v[210:213], v[102:105]
	v_mfma_f32_16x16x32_bf16 v[98:101], v[154:157], v[210:213], v[98:101]
	v_mfma_f32_16x16x32_bf16 v[126:129], v[150:153], v[190:193], v[126:129]
	v_mfma_f32_16x16x32_bf16 v[122:125], v[158:161], v[190:193], v[122:125]
	v_mfma_f32_16x16x32_bf16 v[118:121], v[150:153], v[198:201], v[118:121]
	v_mfma_f32_16x16x32_bf16 v[114:117], v[158:161], v[198:201], v[114:117]
	v_mfma_f32_16x16x32_bf16 v[110:113], v[150:153], v[206:209], v[110:113]
	v_mfma_f32_16x16x32_bf16 v[106:109], v[158:161], v[206:209], v[106:109]
	v_mfma_f32_16x16x32_bf16 v[102:105], v[150:153], v[214:217], v[102:105]
	v_mfma_f32_16x16x32_bf16 v[98:101], v[158:161], v[214:217], v[98:101]
	v_mfma_f32_16x16x32_bf16 v[94:97], v[168:171], v[186:189], v[94:97]
	v_mfma_f32_16x16x32_bf16 v[90:93], v[176:179], v[186:189], v[90:93]
	v_mfma_f32_16x16x32_bf16 v[86:89], v[168:171], v[194:197], v[86:89]
	v_mfma_f32_16x16x32_bf16 v[82:85], v[176:179], v[194:197], v[82:85]
	v_mfma_f32_16x16x32_bf16 v[78:81], v[168:171], v[202:205], v[78:81]
	v_mfma_f32_16x16x32_bf16 v[74:77], v[176:179], v[202:205], v[74:77]
	v_mfma_f32_16x16x32_bf16 v[70:73], v[168:171], v[210:213], v[70:73]
	v_mfma_f32_16x16x32_bf16 v[66:69], v[176:179], v[210:213], v[66:69]
	v_mfma_f32_16x16x32_bf16 v[94:97], v[172:175], v[190:193], v[94:97]
	v_mfma_f32_16x16x32_bf16 v[90:93], v[180:183], v[190:193], v[90:93]
	v_mfma_f32_16x16x32_bf16 v[86:89], v[172:175], v[198:201], v[86:89]
	v_mfma_f32_16x16x32_bf16 v[82:85], v[180:183], v[198:201], v[82:85]
	v_mfma_f32_16x16x32_bf16 v[78:81], v[172:175], v[206:209], v[78:81]
	v_mfma_f32_16x16x32_bf16 v[74:77], v[180:183], v[206:209], v[74:77]
	v_mfma_f32_16x16x32_bf16 v[70:73], v[172:175], v[214:217], v[70:73]
	v_mfma_f32_16x16x32_bf16 v[66:69], v[180:183], v[214:217], v[66:69]
	s_setprio 0
	s_barrier
	s_add_u32 s88, s46, s20
	s_addc_u32 s89, s47, s21
	s_add_u32 s90, s48, s20
	s_addc_u32 s91, s49, s21
	s_add_i32 s73, s64, s52
	s_mov_b32 m0, s73
	ds_read_b128 v[186:189], v167 offset:16384
	ds_read_b128 v[190:193], v167 offset:17408
	ds_read_b128 v[194:197], v167 offset:18432
	ds_read_b128 v[198:201], v167 offset:19456
	ds_read_b128 v[202:205], v167 offset:20480
	ds_read_b128 v[206:209], v167 offset:21504
	ds_read_b128 v[210:213], v167 offset:22528
	ds_read_b128 v[214:217], v167 offset:23552
	global_load_lds_dwordx4 v132, s[46:47]
	s_add_i32 m0, s73, 0x2000
	s_add_u32 s74, s46, 0x20000
	s_addc_u32 s75, s47, 0
	s_add_i32 s73, s65, s52
	global_load_lds_dwordx4 v136, s[46:47]
	s_mov_b32 m0, s73
	s_nop 0
	global_load_lds_dwordx4 v132, s[74:75]
	s_add_i32 m0, s73, 0x2000
	s_nop 0
	global_load_lds_dwordx4 v136, s[74:75]
	s_mov_b32 m0, s53
	s_nop 0
	global_load_lds_dwordx4 v130, s[48:49]
	s_mov_b32 m0, s54
	s_nop 0
	global_load_lds_dwordx4 v134, s[48:49]
	s_cmp_lg_u32 s99, 0
	s_cbranch_scc1 .Lpk3_w2
	s_waitcnt vmcnt(8)
.Lpk3_w2:
	s_mov_b32 s99, 0
	s_waitcnt lgkmcnt(0)
	s_barrier
	s_setprio 1
	v_mfma_f32_16x16x32_bf16 v[62:65], v[146:149], v[186:189], v[62:65]
	v_mfma_f32_16x16x32_bf16 v[58:61], v[154:157], v[186:189], v[58:61]
	v_mfma_f32_16x16x32_bf16 v[54:57], v[146:149], v[194:197], v[54:57]
	v_mfma_f32_16x16x32_bf16 v[50:53], v[154:157], v[194:197], v[50:53]
	v_mfma_f32_16x16x32_bf16 v[46:49], v[146:149], v[202:205], v[46:49]
	v_mfma_f32_16x16x32_bf16 v[42:45], v[154:157], v[202:205], v[42:45]
	v_mfma_f32_16x16x32_bf16 v[38:41], v[146:149], v[210:213], v[38:41]
	v_mfma_f32_16x16x32_bf16 v[34:37], v[154:157], v[210:213], v[34:37]
	v_mfma_f32_16x16x32_bf16 v[62:65], v[150:153], v[190:193], v[62:65]
	v_mfma_f32_16x16x32_bf16 v[58:61], v[158:161], v[190:193], v[58:61]
	v_mfma_f32_16x16x32_bf16 v[54:57], v[150:153], v[198:201], v[54:57]
	v_mfma_f32_16x16x32_bf16 v[50:53], v[158:161], v[198:201], v[50:53]
	v_mfma_f32_16x16x32_bf16 v[46:49], v[150:153], v[206:209], v[46:49]
	v_mfma_f32_16x16x32_bf16 v[42:45], v[158:161], v[206:209], v[42:45]
	v_mfma_f32_16x16x32_bf16 v[38:41], v[150:153], v[214:217], v[38:41]
	v_mfma_f32_16x16x32_bf16 v[34:37], v[158:161], v[214:217], v[34:37]
	v_mfma_f32_16x16x32_bf16 v[30:33], v[168:171], v[186:189], v[30:33]
	v_mfma_f32_16x16x32_bf16 v[26:29], v[176:179], v[186:189], v[26:29]
	v_mfma_f32_16x16x32_bf16 v[22:25], v[168:171], v[194:197], v[22:25]
	v_mfma_f32_16x16x32_bf16 v[18:21], v[176:179], v[194:197], v[18:21]
	v_mfma_f32_16x16x32_bf16 v[14:17], v[168:171], v[202:205], v[14:17]
	v_mfma_f32_16x16x32_bf16 v[10:13], v[176:179], v[202:205], v[10:13]
	v_mfma_f32_16x16x32_bf16 v[6:9], v[168:171], v[210:213], v[6:9]
	v_mfma_f32_16x16x32_bf16 v[2:5], v[176:179], v[210:213], v[2:5]
	v_mfma_f32_16x16x32_bf16 v[30:33], v[172:175], v[190:193], v[30:33]
	v_mfma_f32_16x16x32_bf16 v[26:29], v[180:183], v[190:193], v[26:29]
	v_mfma_f32_16x16x32_bf16 v[22:25], v[172:175], v[198:201], v[22:25]
	v_mfma_f32_16x16x32_bf16 v[18:21], v[180:183], v[198:201], v[18:21]
	v_mfma_f32_16x16x32_bf16 v[14:17], v[172:175], v[206:209], v[14:17]
	v_mfma_f32_16x16x32_bf16 v[10:13], v[180:183], v[206:209], v[10:13]
	v_mfma_f32_16x16x32_bf16 v[6:9], v[172:175], v[214:217], v[6:9]
	v_mfma_f32_16x16x32_bf16 v[2:5], v[180:183], v[214:217], v[2:5]
	s_setprio 0
	s_barrier
; #define PG8_STAGE(bufoff, gbase, voff) do { _Pragma("unroll") for (int _i = 0; _i < 2; ++_i) \
;         __builtin_amdgcn_global_load_lds((const unsigned*)((const char*)(gbase) + (voff)[_i]), (LAS unsigned*)(lds + (bufoff) + ldsw + _i * 8192), 16, 0, 0); } while (0)
; #define PG8_LDA(dst, b, h) do { _Pragma("unroll") for (int m = 0; m < 4; ++m) _Pragma("unroll") for (int k = 0; k < 2; ++k) dst[m][k] = *(const LAS bf16x8*)(lds + PG8_SA(b, h) + aoff + m * 2048 + k * 1024); } while (0)
; #define PG8_LDB(dst, b, h) do { _Pragma("unroll") for (int n = 0; n < 2; ++n) _Pragma("unroll") for (int k = 0; k < 2; ++k) dst[n][k] = *(const LAS bf16x8*)(lds + PG8_SB(b, h) + boff + n * 2048 + k * 1024); } while (0)
; #define PG8_MMA(ai, bj, At, Bt) do { __builtin_amdgcn_s_setprio(1); _Pragma("unroll") for (int m = 0; m < 4; ++m) _Pragma("unroll") for (int n = 0; n < 2; ++n) _Pragma("unroll") for (int k = 0; k < 2; ++k) \
;         acc[ai][bj][m][n] = __builtin_amdgcn_mfma_f32_16x16x32_bf16(Bt[n][k], At[m][k], acc[ai][bj][m][n], 0, 0, 0); __builtin_amdgcn_s_setprio(0); } while (0)
; #define PG8_WAIT_V(n) asm volatile("s_waitcnt vmcnt(" #n ")" ::: "memory")
; #define PG8_WAIT_L(n) asm volatile("s_waitcnt lgkmcnt(" #n ")" ::: "memory")
; #define PG8_BAR __builtin_amdgcn_s_barrier()
; #define PG8_SCHED __builtin_amdgcn_sched_barrier(0)
; template <class Epi, class Sched>
; DI void gemm_phase(LAS unsigned char* lds, const Gemm g, const Sched& S, const Epi& E) {
;     ...
;             PG8_LDB(B0, 1, 0); PG8_LDB(B1, 1, 1); PG8_SCHED; PG8_LDA(At, 1, 0); PG8_STAGE(PG8_SA(0, 1), a2 + hstepA, voffA);
;             PG8_WAIT_V(8); PG8_WAIT_L(0); PG8_BAR; PG8_MMA(0, 0, At, B0); PG8_MMA(0, 1, At, B1); PG8_BAR; PG8_SCHED;
;             PG8_LDA(At, 1, 1); PG8_STAGE(PG8_SB(1, 0), b3, voffB); PG8_STAGE(PG8_SB(1, 1), b3 + hstepB, voffB); PG8_STAGE(PG8_SA(1, 0), a3, voffA);
;             PG8_WAIT_V(8); PG8_WAIT_L(0); PG8_BAR; PG8_MMA(1, 0, At, B0); PG8_MMA(1, 1, At, B1); PG8_BAR; PG8_SCHED;
	s_add_i32 s73, 0, 0x18000
	s_add_i32 s74, 0, 0x1c000
	v_add_u32_e32 v158, s73, v162
	v_add_u32_e32 v180, s74, v162
	ds_read_b128 v[146:149], v158
	ds_read_b128 v[150:153], v158 offset:1024
	ds_read_b128 v[154:157], v158 offset:2048
	ds_read_b128 v[158:161], v158 offset:3072
	ds_read_b128 v[168:171], v180
	ds_read_b128 v[172:175], v180 offset:1024
	ds_read_b128 v[176:179], v180 offset:2048
	ds_read_b128 v[180:183], v180 offset:3072
	s_add_u32 s48, s48, 0x20000
	s_addc_u32 s49, s49, 0
	s_mov_b32 m0, s55
	ds_read_b128 v[186:189], v167 offset:32768
	ds_read_b128 v[190:193], v167 offset:33792
	ds_read_b128 v[194:197], v167 offset:34816
	ds_read_b128 v[198:201], v167 offset:35840
	ds_read_b128 v[202:205], v167 offset:36864
	ds_read_b128 v[206:209], v167 offset:37888
	ds_read_b128 v[210:213], v167 offset:38912
	ds_read_b128 v[214:217], v167 offset:39936
	global_load_lds_dwordx4 v130, s[48:49]
	s_mov_b32 m0, s56
	s_nop 0
	global_load_lds_dwordx4 v134, s[48:49]
	s_waitcnt vmcnt(8)
	s_waitcnt lgkmcnt(0)
	s_barrier
	s_setprio 1
	v_mfma_f32_16x16x32_bf16 v[126:129], v[146:149], v[186:189], v[126:129]
	v_mfma_f32_16x16x32_bf16 v[122:125], v[154:157], v[186:189], v[122:125]
	v_mfma_f32_16x16x32_bf16 v[118:121], v[146:149], v[194:197], v[118:121]
	v_mfma_f32_16x16x32_bf16 v[114:117], v[154:157], v[194:197], v[114:117]
	v_mfma_f32_16x16x32_bf16 v[110:113], v[146:149], v[202:205], v[110:113]
	v_mfma_f32_16x16x32_bf16 v[106:109], v[154:157], v[202:205], v[106:109]
	v_mfma_f32_16x16x32_bf16 v[102:105], v[146:149], v[210:213], v[102:105]
	v_mfma_f32_16x16x32_bf16 v[98:101], v[154:157], v[210:213], v[98:101]
	v_mfma_f32_16x16x32_bf16 v[126:129], v[150:153], v[190:193], v[126:129]
	v_mfma_f32_16x16x32_bf16 v[122:125], v[158:161], v[190:193], v[122:125]
	v_mfma_f32_16x16x32_bf16 v[118:121], v[150:153], v[198:201], v[118:121]
	v_mfma_f32_16x16x32_bf16 v[114:117], v[158:161], v[198:201], v[114:117]
	v_mfma_f32_16x16x32_bf16 v[110:113], v[150:153], v[206:209], v[110:113]
	v_mfma_f32_16x16x32_bf16 v[106:109], v[158:161], v[206:209], v[106:109]
	v_mfma_f32_16x16x32_bf16 v[102:105], v[150:153], v[214:217], v[102:105]
	v_mfma_f32_16x16x32_bf16 v[98:101], v[158:161], v[214:217], v[98:101]
	v_mfma_f32_16x16x32_bf16 v[94:97], v[168:171], v[186:189], v[94:97]
	v_mfma_f32_16x16x32_bf16 v[90:93], v[176:179], v[186:189], v[90:93]
	v_mfma_f32_16x16x32_bf16 v[86:89], v[168:171], v[194:197], v[86:89]
	v_mfma_f32_16x16x32_bf16 v[82:85], v[176:179], v[194:197], v[82:85]
	v_mfma_f32_16x16x32_bf16 v[78:81], v[168:171], v[202:205], v[78:81]
	v_mfma_f32_16x16x32_bf16 v[74:77], v[176:179], v[202:205], v[74:77]
	v_mfma_f32_16x16x32_bf16 v[70:73], v[168:171], v[210:213], v[70:73]
	v_mfma_f32_16x16x32_bf16 v[66:69], v[176:179], v[210:213], v[66:69]
	v_mfma_f32_16x16x32_bf16 v[94:97], v[172:175], v[190:193], v[94:97]
	v_mfma_f32_16x16x32_bf16 v[90:93], v[180:183], v[190:193], v[90:93]
	v_mfma_f32_16x16x32_bf16 v[86:89], v[172:175], v[198:201], v[86:89]
	v_mfma_f32_16x16x32_bf16 v[82:85], v[180:183], v[198:201], v[82:85]
	v_mfma_f32_16x16x32_bf16 v[78:81], v[172:175], v[206:209], v[78:81]
	v_mfma_f32_16x16x32_bf16 v[74:77], v[180:183], v[206:209], v[74:77]
	v_mfma_f32_16x16x32_bf16 v[70:73], v[172:175], v[214:217], v[70:73]
	v_mfma_f32_16x16x32_bf16 v[66:69], v[180:183], v[214:217], v[66:69]
	s_setprio 0
	s_barrier
	s_add_i32 s48, s73, s52
	s_mov_b32 m0, s48
	ds_read_b128 v[186:189], v167 offset:49152
	ds_read_b128 v[190:193], v167 offset:50176
	ds_read_b128 v[194:197], v167 offset:51200
	ds_read_b128 v[198:201], v167 offset:52224
	ds_read_b128 v[202:205], v167 offset:53248
	ds_read_b128 v[206:209], v167 offset:54272
	ds_read_b128 v[210:213], v167 offset:55296
	ds_read_b128 v[214:217], v167 offset:56320
	global_load_lds_dwordx4 v132, s[88:89]
	s_add_i32 m0, s48, 0x2000
	s_add_u32 s46, s46, 0x20080
	s_addc_u32 s47, s47, 0
	s_add_i32 s48, s74, s52
	global_load_lds_dwordx4 v136, s[88:89]
	s_mov_b32 m0, s48
	s_nop 0
	global_load_lds_dwordx4 v132, s[46:47]
	s_add_i32 m0, s48, 0x2000
	s_nop 0
	global_load_lds_dwordx4 v136, s[46:47]
	s_mov_b32 m0, s61
	s_nop 0
	global_load_lds_dwordx4 v130, s[90:91]
	s_mov_b32 m0, s62
	s_nop 0
	global_load_lds_dwordx4 v134, s[90:91]
	s_waitcnt vmcnt(8)
	s_waitcnt lgkmcnt(0)
	s_barrier
	s_setprio 1
	v_mfma_f32_16x16x32_bf16 v[62:65], v[146:149], v[186:189], v[62:65]
	v_mfma_f32_16x16x32_bf16 v[58:61], v[154:157], v[186:189], v[58:61]
	v_mfma_f32_16x16x32_bf16 v[54:57], v[146:149], v[194:197], v[54:57]
	v_mfma_f32_16x16x32_bf16 v[50:53], v[154:157], v[194:197], v[50:53]
	v_mfma_f32_16x16x32_bf16 v[46:49], v[146:149], v[202:205], v[46:49]
	v_mfma_f32_16x16x32_bf16 v[42:45], v[154:157], v[202:205], v[42:45]
	v_mfma_f32_16x16x32_bf16 v[38:41], v[146:149], v[210:213], v[38:41]
	v_mfma_f32_16x16x32_bf16 v[34:37], v[154:157], v[210:213], v[34:37]
	v_mfma_f32_16x16x32_bf16 v[62:65], v[150:153], v[190:193], v[62:65]
	v_mfma_f32_16x16x32_bf16 v[58:61], v[158:161], v[190:193], v[58:61]
	v_mfma_f32_16x16x32_bf16 v[54:57], v[150:153], v[198:201], v[54:57]
	v_mfma_f32_16x16x32_bf16 v[50:53], v[158:161], v[198:201], v[50:53]
	v_mfma_f32_16x16x32_bf16 v[46:49], v[150:153], v[206:209], v[46:49]
	v_mfma_f32_16x16x32_bf16 v[42:45], v[158:161], v[206:209], v[42:45]
	v_mfma_f32_16x16x32_bf16 v[38:41], v[150:153], v[214:217], v[38:41]
	v_mfma_f32_16x16x32_bf16 v[34:37], v[158:161], v[214:217], v[34:37]
	v_mfma_f32_16x16x32_bf16 v[30:33], v[168:171], v[186:189], v[30:33]
	v_mfma_f32_16x16x32_bf16 v[26:29], v[176:179], v[186:189], v[26:29]
	v_mfma_f32_16x16x32_bf16 v[22:25], v[168:171], v[194:197], v[22:25]
	v_mfma_f32_16x16x32_bf16 v[18:21], v[176:179], v[194:197], v[18:21]
	v_mfma_f32_16x16x32_bf16 v[14:17], v[168:171], v[202:205], v[14:17]
	v_mfma_f32_16x16x32_bf16 v[10:13], v[176:179], v[202:205], v[10:13]
	v_mfma_f32_16x16x32_bf16 v[6:9], v[168:171], v[210:213], v[6:9]
	v_mfma_f32_16x16x32_bf16 v[2:5], v[176:179], v[210:213], v[2:5]
	v_mfma_f32_16x16x32_bf16 v[30:33], v[172:175], v[190:193], v[30:33]
	v_mfma_f32_16x16x32_bf16 v[26:29], v[180:183], v[190:193], v[26:29]
	v_mfma_f32_16x16x32_bf16 v[22:25], v[172:175], v[198:201], v[22:25]
	v_mfma_f32_16x16x32_bf16 v[18:21], v[180:183], v[198:201], v[18:21]
	v_mfma_f32_16x16x32_bf16 v[14:17], v[172:175], v[206:209], v[14:17]
	v_mfma_f32_16x16x32_bf16 v[10:13], v[180:183], v[206:209], v[10:13]
	v_mfma_f32_16x16x32_bf16 v[6:9], v[172:175], v[214:217], v[6:9]
	v_mfma_f32_16x16x32_bf16 v[2:5], v[180:183], v[214:217], v[2:5]
	s_setprio 0
	s_barrier
	s_add_i32 s72, s72, 2
	s_add_u32 s44, s44, 0x100
	s_addc_u32 s45, s45, 0
	s_add_u32 s70, s70, 0x100
	s_addc_u32 s71, s71, 0
	s_cmp_gt_u32 s72, 5
; #define PG8_STAGE(bufoff, gbase, voff) do { _Pragma("unroll") for (int _i = 0; _i < 2; ++_i) \
;         __builtin_amdgcn_global_load_lds((const unsigned*)((const char*)(gbase) + (voff)[_i]), (LAS unsigned*)(lds + (bufoff) + ldsw + _i * 8192), 16, 0, 0); } while (0)
; #define PG8_LDA(dst, b, h) do { _Pragma("unroll") for (int m = 0; m < 4; ++m) _Pragma("unroll") for (int k = 0; k < 2; ++k) dst[m][k] = *(const LAS bf16x8*)(lds + PG8_SA(b, h) + aoff + m * 2048 + k * 1024); } while (0)
; #define PG8_LDB(dst, b, h) do { _Pragma("unroll") for (int n = 0; n < 2; ++n) _Pragma("unroll") for (int k = 0; k < 2; ++k) dst[n][k] = *(const LAS bf16x8*)(lds + PG8_SB(b, h) + boff + n * 2048 + k * 1024); } while (0)
; #define PG8_MMA(ai, bj, At, Bt) do { __builtin_amdgcn_s_setprio(1); _Pragma("unroll") for (int m = 0; m < 4; ++m) _Pragma("unroll") for (int n = 0; n < 2; ++n) _Pragma("unroll") for (int k = 0; k < 2; ++k) \
;         acc[ai][bj][m][n] = __builtin_amdgcn_mfma_f32_16x16x32_bf16(Bt[n][k], At[m][k], acc[ai][bj][m][n], 0, 0, 0); __builtin_amdgcn_s_setprio(0); } while (0)
; #define PG8_WAIT_V(n) asm volatile("s_waitcnt vmcnt(" #n ")" ::: "memory")
; #define PG8_WAIT_L(n) asm volatile("s_waitcnt lgkmcnt(" #n ")" ::: "memory")
; #define PG8_BAR __builtin_amdgcn_s_barrier()
; #define PG8_SCHED __builtin_amdgcn_sched_barrier(0)
; template <class Epi, class Sched>
; DI void gemm_phase(LAS unsigned char* lds, const Gemm g, const Sched& S, const Epi& E) {
;     ...
;             const bool last = (t == nt - 2);
;             const char* a1 = cA + (size_t)(t + 1) * kstep;
;             const char* a2 = last ? nA : cA + (size_t)(t + 2) * kstep; const char* b2 = last ? nB : cB + (size_t)(t + 2) * kstep;
;             const char* a3 = a2 + kstep; const char* b3 = b2 + kstep;
;             PG8_LDB(B0, 0, 0); PG8_LDB(B1, 0, 1); PG8_SCHED; PG8_LDA(At, 0, 0); PG8_STAGE(PG8_SA(1, 1), a1 + hstepA, voffA);
;             PG8_WAIT_V(8); PG8_WAIT_L(0); PG8_BAR; PG8_MMA(0, 0, At, B0); PG8_MMA(0, 1, At, B1); PG8_BAR; PG8_SCHED;
;             PG8_LDA(At, 0, 1); PG8_STAGE(PG8_SB(0, 0), b2, voffB); PG8_STAGE(PG8_SB(0, 1), b2 + hstepB, voffB); PG8_STAGE(PG8_SA(0, 0), a2, voffA);
;             PG8_WAIT_V(8); PG8_WAIT_L(0); PG8_BAR; PG8_MMA(1, 0, At, B0); PG8_MMA(1, 1, At, B1); PG8_BAR; PG8_SCHED;
.LBB0_972:
	v_add_u32_e32 v158, s64, v162
	v_add_u32_e32 v180, s65, v162
	ds_read_b128 v[146:149], v158
	ds_read_b128 v[150:153], v158 offset:1024
	ds_read_b128 v[154:157], v158 offset:2048
	ds_read_b128 v[158:161], v158 offset:3072
	ds_read_b128 v[168:171], v180
	ds_read_b128 v[172:175], v180 offset:1024
	ds_read_b128 v[176:179], v180 offset:2048
	ds_read_b128 v[180:183], v180 offset:3072
	s_add_u32 s46, s44, 0xfffe0080
	s_addc_u32 s47, s45, -1
	s_cmp_eq_u32 s72, 4
	s_cselect_b32 s49, s39, s47
	s_cselect_b32 s48, s68, s46
	s_cselect_b32 s47, s37, s71
	s_cselect_b32 s46, s69, s70
	s_add_i32 m0, s53, 0xc000
	ds_read_b128 v[186:189], v167
	ds_read_b128 v[190:193], v167 offset:1024
	ds_read_b128 v[194:197], v167 offset:2048
	ds_read_b128 v[198:201], v167 offset:3072
	ds_read_b128 v[202:205], v167 offset:4096
	ds_read_b128 v[206:209], v167 offset:5120
	ds_read_b128 v[210:213], v167 offset:6144
	ds_read_b128 v[214:217], v167 offset:7168
	global_load_lds_dwordx4 v138, s[44:45]
	s_add_i32 m0, s53, 0xe000
	s_nop 0
	global_load_lds_dwordx4 v140, s[44:45]
	s_waitcnt vmcnt(8)
	s_waitcnt lgkmcnt(0)
	s_barrier
	s_setprio 1
	v_mfma_f32_16x16x32_bf16 v[126:129], v[146:149], v[186:189], v[126:129]
	v_mfma_f32_16x16x32_bf16 v[122:125], v[154:157], v[186:189], v[122:125]
	v_mfma_f32_16x16x32_bf16 v[118:121], v[146:149], v[194:197], v[118:121]
	v_mfma_f32_16x16x32_bf16 v[114:117], v[154:157], v[194:197], v[114:117]
	v_mfma_f32_16x16x32_bf16 v[110:113], v[146:149], v[202:205], v[110:113]
	v_mfma_f32_16x16x32_bf16 v[106:109], v[154:157], v[202:205], v[106:109]
	v_mfma_f32_16x16x32_bf16 v[102:105], v[146:149], v[210:213], v[102:105]
	v_mfma_f32_16x16x32_bf16 v[98:101], v[154:157], v[210:213], v[98:101]
	v_mfma_f32_16x16x32_bf16 v[126:129], v[150:153], v[190:193], v[126:129]
	v_mfma_f32_16x16x32_bf16 v[122:125], v[158:161], v[190:193], v[122:125]
	v_mfma_f32_16x16x32_bf16 v[118:121], v[150:153], v[198:201], v[118:121]
	v_mfma_f32_16x16x32_bf16 v[114:117], v[158:161], v[198:201], v[114:117]
	v_mfma_f32_16x16x32_bf16 v[110:113], v[150:153], v[206:209], v[110:113]
	v_mfma_f32_16x16x32_bf16 v[106:109], v[158:161], v[206:209], v[106:109]
	v_mfma_f32_16x16x32_bf16 v[102:105], v[150:153], v[214:217], v[102:105]
	v_mfma_f32_16x16x32_bf16 v[98:101], v[158:161], v[214:217], v[98:101]
	v_mfma_f32_16x16x32_bf16 v[94:97], v[168:171], v[186:189], v[94:97]
	v_mfma_f32_16x16x32_bf16 v[90:93], v[176:179], v[186:189], v[90:93]
	v_mfma_f32_16x16x32_bf16 v[86:89], v[168:171], v[194:197], v[86:89]
	v_mfma_f32_16x16x32_bf16 v[82:85], v[176:179], v[194:197], v[82:85]
	v_mfma_f32_16x16x32_bf16 v[78:81], v[168:171], v[202:205], v[78:81]
	v_mfma_f32_16x16x32_bf16 v[74:77], v[176:179], v[202:205], v[74:77]
	v_mfma_f32_16x16x32_bf16 v[70:73], v[168:171], v[210:213], v[70:73]
	v_mfma_f32_16x16x32_bf16 v[66:69], v[176:179], v[210:213], v[66:69]
	v_mfma_f32_16x16x32_bf16 v[94:97], v[172:175], v[190:193], v[94:97]
	v_mfma_f32_16x16x32_bf16 v[90:93], v[180:183], v[190:193], v[90:93]
	v_mfma_f32_16x16x32_bf16 v[86:89], v[172:175], v[198:201], v[86:89]
	v_mfma_f32_16x16x32_bf16 v[82:85], v[180:183], v[198:201], v[82:85]
	v_mfma_f32_16x16x32_bf16 v[78:81], v[172:175], v[206:209], v[78:81]
	v_mfma_f32_16x16x32_bf16 v[74:77], v[180:183], v[206:209], v[74:77]
	v_mfma_f32_16x16x32_bf16 v[70:73], v[172:175], v[214:217], v[70:73]
	v_mfma_f32_16x16x32_bf16 v[66:69], v[180:183], v[214:217], v[66:69]
	s_setprio 0
	s_barrier
	s_add_u32 s88, s46, s20
	s_addc_u32 s89, s47, s21
	s_add_u32 s90, s48, s20
	s_addc_u32 s91, s49, s21
	s_add_i32 s73, s64, s52
	s_mov_b32 m0, s73
	ds_read_b128 v[186:189], v167 offset:16384
	ds_read_b128 v[190:193], v167 offset:17408
	ds_read_b128 v[194:197], v167 offset:18432
	ds_read_b128 v[198:201], v167 offset:19456
	ds_read_b128 v[202:205], v167 offset:20480
	ds_read_b128 v[206:209], v167 offset:21504
	ds_read_b128 v[210:213], v167 offset:22528
	ds_read_b128 v[214:217], v167 offset:23552
	global_load_lds_dwordx4 v132, s[46:47]
	s_add_i32 m0, s73, 0x2000
	s_add_u32 s74, s46, 0x20000
	s_addc_u32 s75, s47, 0
	s_add_i32 s73, s65, s52
	global_load_lds_dwordx4 v136, s[46:47]
	s_mov_b32 m0, s73
	s_nop 0
	global_load_lds_dwordx4 v132, s[74:75]
	s_add_i32 m0, s73, 0x2000
	s_nop 0
	global_load_lds_dwordx4 v136, s[74:75]
	s_mov_b32 m0, s53
	s_nop 0
	global_load_lds_dwordx4 v130, s[48:49]
	s_mov_b32 m0, s54
	s_nop 0
	global_load_lds_dwordx4 v134, s[48:49]
	s_waitcnt vmcnt(8)
	s_waitcnt lgkmcnt(0)
	s_barrier
	s_setprio 1
	v_mfma_f32_16x16x32_bf16 v[62:65], v[146:149], v[186:189], v[62:65]
	v_mfma_f32_16x16x32_bf16 v[58:61], v[154:157], v[186:189], v[58:61]
	v_mfma_f32_16x16x32_bf16 v[54:57], v[146:149], v[194:197], v[54:57]
	v_mfma_f32_16x16x32_bf16 v[50:53], v[154:157], v[194:197], v[50:53]
	v_mfma_f32_16x16x32_bf16 v[46:49], v[146:149], v[202:205], v[46:49]
	v_mfma_f32_16x16x32_bf16 v[42:45], v[154:157], v[202:205], v[42:45]
	v_mfma_f32_16x16x32_bf16 v[38:41], v[146:149], v[210:213], v[38:41]
	v_mfma_f32_16x16x32_bf16 v[34:37], v[154:157], v[210:213], v[34:37]
	v_mfma_f32_16x16x32_bf16 v[62:65], v[150:153], v[190:193], v[62:65]
	v_mfma_f32_16x16x32_bf16 v[58:61], v[158:161], v[190:193], v[58:61]
	v_mfma_f32_16x16x32_bf16 v[54:57], v[150:153], v[198:201], v[54:57]
	v_mfma_f32_16x16x32_bf16 v[50:53], v[158:161], v[198:201], v[50:53]
	v_mfma_f32_16x16x32_bf16 v[46:49], v[150:153], v[206:209], v[46:49]
	v_mfma_f32_16x16x32_bf16 v[42:45], v[158:161], v[206:209], v[42:45]
	v_mfma_f32_16x16x32_bf16 v[38:41], v[150:153], v[214:217], v[38:41]
	v_mfma_f32_16x16x32_bf16 v[34:37], v[158:161], v[214:217], v[34:37]
	v_mfma_f32_16x16x32_bf16 v[30:33], v[168:171], v[186:189], v[30:33]
	v_mfma_f32_16x16x32_bf16 v[26:29], v[176:179], v[186:189], v[26:29]
	v_mfma_f32_16x16x32_bf16 v[22:25], v[168:171], v[194:197], v[22:25]
	v_mfma_f32_16x16x32_bf16 v[18:21], v[176:179], v[194:197], v[18:21]
	v_mfma_f32_16x16x32_bf16 v[14:17], v[168:171], v[202:205], v[14:17]
	v_mfma_f32_16x16x32_bf16 v[10:13], v[176:179], v[202:205], v[10:13]
	v_mfma_f32_16x16x32_bf16 v[6:9], v[168:171], v[210:213], v[6:9]
	v_mfma_f32_16x16x32_bf16 v[2:5], v[176:179], v[210:213], v[2:5]
	v_mfma_f32_16x16x32_bf16 v[30:33], v[172:175], v[190:193], v[30:33]
	v_mfma_f32_16x16x32_bf16 v[26:29], v[180:183], v[190:193], v[26:29]
	v_mfma_f32_16x16x32_bf16 v[22:25], v[172:175], v[198:201], v[22:25]
	v_mfma_f32_16x16x32_bf16 v[18:21], v[180:183], v[198:201], v[18:21]
	v_mfma_f32_16x16x32_bf16 v[14:17], v[172:175], v[206:209], v[14:17]
	v_mfma_f32_16x16x32_bf16 v[10:13], v[180:183], v[206:209], v[10:13]
	v_mfma_f32_16x16x32_bf16 v[6:9], v[172:175], v[214:217], v[6:9]
	v_mfma_f32_16x16x32_bf16 v[2:5], v[180:183], v[214:217], v[2:5]
	s_setprio 0
	s_barrier
; #define PG8_STAGE(bufoff, gbase, voff) do { _Pragma("unroll") for (int _i = 0; _i < 2; ++_i) \
;         __builtin_amdgcn_global_load_lds((const unsigned*)((const char*)(gbase) + (voff)[_i]), (LAS unsigned*)(lds + (bufoff) + ldsw + _i * 8192), 16, 0, 0); } while (0)
; #define PG8_LDA(dst, b, h) do { _Pragma("unroll") for (int m = 0; m < 4; ++m) _Pragma("unroll") for (int k = 0; k < 2; ++k) dst[m][k] = *(const LAS bf16x8*)(lds + PG8_SA(b, h) + aoff + m * 2048 + k * 1024); } while (0)
; #define PG8_LDB(dst, b, h) do { _Pragma("unroll") for (int n = 0; n < 2; ++n) _Pragma("unroll") for (int k = 0; k < 2; ++k) dst[n][k] = *(const LAS bf16x8*)(lds + PG8_SB(b, h) + boff + n * 2048 + k * 1024); } while (0)
; #define PG8_MMA(ai, bj, At, Bt) do { __builtin_amdgcn_s_setprio(1); _Pragma("unroll") for (int m = 0; m < 4; ++m) _Pragma("unroll") for (int n = 0; n < 2; ++n) _Pragma("unroll") for (int k = 0; k < 2; ++k) \
;         acc[ai][bj][m][n] = __builtin_amdgcn_mfma_f32_16x16x32_bf16(Bt[n][k], At[m][k], acc[ai][bj][m][n], 0, 0, 0); __builtin_amdgcn_s_setprio(0); } while (0)
; #define PG8_WAIT_V(n) asm volatile("s_waitcnt vmcnt(" #n ")" ::: "memory")
; #define PG8_WAIT_L(n) asm volatile("s_waitcnt lgkmcnt(" #n ")" ::: "memory")
; #define PG8_BAR __builtin_amdgcn_s_barrier()
; #define PG8_SCHED __builtin_amdgcn_sched_barrier(0)
; template <class Epi, class Sched>
; DI void gemm_phase(LAS unsigned char* lds, const Gemm g, const Sched& S, const Epi& E) {
;     ...
;             PG8_LDB(B0, 1, 0); PG8_LDB(B1, 1, 1); PG8_SCHED; PG8_LDA(At, 1, 0); PG8_STAGE(PG8_SA(0, 1), a2 + hstepA, voffA);
;             PG8_WAIT_V(8); PG8_WAIT_L(0); PG8_BAR; PG8_MMA(0, 0, At, B0); PG8_MMA(0, 1, At, B1); PG8_BAR; PG8_SCHED;
;             PG8_LDA(At, 1, 1); PG8_STAGE(PG8_SB(1, 0), b3, voffB); PG8_STAGE(PG8_SB(1, 1), b3 + hstepB, voffB); PG8_STAGE(PG8_SA(1, 0), a3, voffA);
;             PG8_WAIT_V(8); PG8_WAIT_L(0); PG8_BAR; PG8_MMA(1, 0, At, B0); PG8_MMA(1, 1, At, B1); PG8_BAR; PG8_SCHED;
;         }
	s_add_i32 s73, 0, 0x18000
	s_add_i32 s74, 0, 0x1c000
	v_add_u32_e32 v158, s73, v162
	v_add_u32_e32 v180, s74, v162
	ds_read_b128 v[146:149], v158
	ds_read_b128 v[150:153], v158 offset:1024
	ds_read_b128 v[154:157], v158 offset:2048
	ds_read_b128 v[158:161], v158 offset:3072
	ds_read_b128 v[168:171], v180
	ds_read_b128 v[172:175], v180 offset:1024
	ds_read_b128 v[176:179], v180 offset:2048
	ds_read_b128 v[180:183], v180 offset:3072
	s_add_u32 s48, s48, 0x20000
	s_addc_u32 s49, s49, 0
	s_mov_b32 m0, s55
	ds_read_b128 v[186:189], v167 offset:32768
	ds_read_b128 v[190:193], v167 offset:33792
	ds_read_b128 v[194:197], v167 offset:34816
	ds_read_b128 v[198:201], v167 offset:35840
	ds_read_b128 v[202:205], v167 offset:36864
	ds_read_b128 v[206:209], v167 offset:37888
	ds_read_b128 v[210:213], v167 offset:38912
	ds_read_b128 v[214:217], v167 offset:39936
	global_load_lds_dwordx4 v130, s[48:49]
	s_mov_b32 m0, s56
	s_nop 0
	global_load_lds_dwordx4 v134, s[48:49]
	s_waitcnt vmcnt(8)
	s_waitcnt lgkmcnt(0)
	s_barrier
	s_setprio 1
	v_mfma_f32_16x16x32_bf16 v[126:129], v[146:149], v[186:189], v[126:129]
	v_mfma_f32_16x16x32_bf16 v[122:125], v[154:157], v[186:189], v[122:125]
	v_mfma_f32_16x16x32_bf16 v[118:121], v[146:149], v[194:197], v[118:121]
	v_mfma_f32_16x16x32_bf16 v[114:117], v[154:157], v[194:197], v[114:117]
	v_mfma_f32_16x16x32_bf16 v[110:113], v[146:149], v[202:205], v[110:113]
	v_mfma_f32_16x16x32_bf16 v[106:109], v[154:157], v[202:205], v[106:109]
	v_mfma_f32_16x16x32_bf16 v[102:105], v[146:149], v[210:213], v[102:105]
	v_mfma_f32_16x16x32_bf16 v[98:101], v[154:157], v[210:213], v[98:101]
	v_mfma_f32_16x16x32_bf16 v[126:129], v[150:153], v[190:193], v[126:129]
	v_mfma_f32_16x16x32_bf16 v[122:125], v[158:161], v[190:193], v[122:125]
	v_mfma_f32_16x16x32_bf16 v[118:121], v[150:153], v[198:201], v[118:121]
	v_mfma_f32_16x16x32_bf16 v[114:117], v[158:161], v[198:201], v[114:117]
	v_mfma_f32_16x16x32_bf16 v[110:113], v[150:153], v[206:209], v[110:113]
	v_mfma_f32_16x16x32_bf16 v[106:109], v[158:161], v[206:209], v[106:109]
	v_mfma_f32_16x16x32_bf16 v[102:105], v[150:153], v[214:217], v[102:105]
	v_mfma_f32_16x16x32_bf16 v[98:101], v[158:161], v[214:217], v[98:101]
	v_mfma_f32_16x16x32_bf16 v[94:97], v[168:171], v[186:189], v[94:97]
	v_mfma_f32_16x16x32_bf16 v[90:93], v[176:179], v[186:189], v[90:93]
	v_mfma_f32_16x16x32_bf16 v[86:89], v[168:171], v[194:197], v[86:89]
	v_mfma_f32_16x16x32_bf16 v[82:85], v[176:179], v[194:197], v[82:85]
	v_mfma_f32_16x16x32_bf16 v[78:81], v[168:171], v[202:205], v[78:81]
	v_mfma_f32_16x16x32_bf16 v[74:77], v[176:179], v[202:205], v[74:77]
	v_mfma_f32_16x16x32_bf16 v[70:73], v[168:171], v[210:213], v[70:73]
	v_mfma_f32_16x16x32_bf16 v[66:69], v[176:179], v[210:213], v[66:69]
	v_mfma_f32_16x16x32_bf16 v[94:97], v[172:175], v[190:193], v[94:97]
	v_mfma_f32_16x16x32_bf16 v[90:93], v[180:183], v[190:193], v[90:93]
	v_mfma_f32_16x16x32_bf16 v[86:89], v[172:175], v[198:201], v[86:89]
	v_mfma_f32_16x16x32_bf16 v[82:85], v[180:183], v[198:201], v[82:85]
	v_mfma_f32_16x16x32_bf16 v[78:81], v[172:175], v[206:209], v[78:81]
	v_mfma_f32_16x16x32_bf16 v[74:77], v[180:183], v[206:209], v[74:77]
	v_mfma_f32_16x16x32_bf16 v[70:73], v[172:175], v[214:217], v[70:73]
	v_mfma_f32_16x16x32_bf16 v[66:69], v[180:183], v[214:217], v[66:69]
	s_setprio 0
	s_barrier
	s_add_i32 s48, s73, s52
	s_mov_b32 m0, s48
	ds_read_b128 v[186:189], v167 offset:49152
	ds_read_b128 v[190:193], v167 offset:50176
	ds_read_b128 v[194:197], v167 offset:51200
	ds_read_b128 v[198:201], v167 offset:52224
	ds_read_b128 v[202:205], v167 offset:53248
	ds_read_b128 v[206:209], v167 offset:54272
	ds_read_b128 v[210:213], v167 offset:55296
	ds_read_b128 v[214:217], v167 offset:56320
	global_load_lds_dwordx4 v132, s[88:89]
	s_add_i32 m0, s48, 0x2000
	s_add_u32 s46, s46, 0x20080
	s_addc_u32 s47, s47, 0
	s_add_i32 s48, s74, s52
	global_load_lds_dwordx4 v136, s[88:89]
	s_mov_b32 m0, s48
	s_nop 0
	global_load_lds_dwordx4 v132, s[46:47]
	s_add_i32 m0, s48, 0x2000
	s_nop 0
	global_load_lds_dwordx4 v136, s[46:47]
	s_mov_b32 m0, s61
	s_nop 0
	global_load_lds_dwordx4 v130, s[90:91]
	s_mov_b32 m0, s62
	s_nop 0
	global_load_lds_dwordx4 v134, s[90:91]
	s_waitcnt vmcnt(8)
	s_waitcnt lgkmcnt(0)
	s_barrier
	s_setprio 1
	v_mfma_f32_16x16x32_bf16 v[62:65], v[146:149], v[186:189], v[62:65]
	v_mfma_f32_16x16x32_bf16 v[58:61], v[154:157], v[186:189], v[58:61]
	v_mfma_f32_16x16x32_bf16 v[54:57], v[146:149], v[194:197], v[54:57]
	v_mfma_f32_16x16x32_bf16 v[50:53], v[154:157], v[194:197], v[50:53]
	v_mfma_f32_16x16x32_bf16 v[46:49], v[146:149], v[202:205], v[46:49]
	v_mfma_f32_16x16x32_bf16 v[42:45], v[154:157], v[202:205], v[42:45]
	v_mfma_f32_16x16x32_bf16 v[38:41], v[146:149], v[210:213], v[38:41]
	v_mfma_f32_16x16x32_bf16 v[34:37], v[154:157], v[210:213], v[34:37]
	v_mfma_f32_16x16x32_bf16 v[62:65], v[150:153], v[190:193], v[62:65]
	v_mfma_f32_16x16x32_bf16 v[58:61], v[158:161], v[190:193], v[58:61]
	v_mfma_f32_16x16x32_bf16 v[54:57], v[150:153], v[198:201], v[54:57]
	v_mfma_f32_16x16x32_bf16 v[50:53], v[158:161], v[198:201], v[50:53]
	v_mfma_f32_16x16x32_bf16 v[46:49], v[150:153], v[206:209], v[46:49]
	v_mfma_f32_16x16x32_bf16 v[42:45], v[158:161], v[206:209], v[42:45]
	v_mfma_f32_16x16x32_bf16 v[38:41], v[150:153], v[214:217], v[38:41]
	v_mfma_f32_16x16x32_bf16 v[34:37], v[158:161], v[214:217], v[34:37]
	v_mfma_f32_16x16x32_bf16 v[30:33], v[168:171], v[186:189], v[30:33]
	v_mfma_f32_16x16x32_bf16 v[26:29], v[176:179], v[186:189], v[26:29]
	v_mfma_f32_16x16x32_bf16 v[22:25], v[168:171], v[194:197], v[22:25]
	v_mfma_f32_16x16x32_bf16 v[18:21], v[176:179], v[194:197], v[18:21]
	v_mfma_f32_16x16x32_bf16 v[14:17], v[168:171], v[202:205], v[14:17]
	v_mfma_f32_16x16x32_bf16 v[10:13], v[176:179], v[202:205], v[10:13]
	v_mfma_f32_16x16x32_bf16 v[6:9], v[168:171], v[210:213], v[6:9]
	v_mfma_f32_16x16x32_bf16 v[2:5], v[176:179], v[210:213], v[2:5]
	v_mfma_f32_16x16x32_bf16 v[30:33], v[172:175], v[190:193], v[30:33]
	v_mfma_f32_16x16x32_bf16 v[26:29], v[180:183], v[190:193], v[26:29]
	v_mfma_f32_16x16x32_bf16 v[22:25], v[172:175], v[198:201], v[22:25]
	v_mfma_f32_16x16x32_bf16 v[18:21], v[180:183], v[198:201], v[18:21]
	v_mfma_f32_16x16x32_bf16 v[14:17], v[172:175], v[206:209], v[14:17]
	v_mfma_f32_16x16x32_bf16 v[10:13], v[180:183], v[206:209], v[10:13]
	v_mfma_f32_16x16x32_bf16 v[6:9], v[172:175], v[214:217], v[6:9]
	v_mfma_f32_16x16x32_bf16 v[2:5], v[180:183], v[214:217], v[2:5]
	s_setprio 0
	s_barrier
	s_add_i32 s72, s72, 2
	s_add_u32 s44, s44, 0x100
	s_addc_u32 s45, s45, 0
	s_add_u32 s70, s70, 0x100
	s_addc_u32 s71, s71, 0
	s_cmp_gt_u32 s72, 5
	s_cbranch_scc0 .LBB0_972
	s_mov_b32 s99, 1
	s_and_b64 vcc, exec, s[34:35]
	s_cbranch_vccz .LBB0_975
	s_barrier
